# FFN up epilogue: row sums of squares fetched by two HBM->LDS DMA loads at tile start and read from LDS (no vmcnt(0) at epilogue start) + conv weight lines touched at epilogue start
# baseline (speedup 1.0000x reference)
; template <class Epi>
; __device__ __forceinline__ void gemm_phase(LAS unsigned char* lds, const Gemm g, const StaticOrder& S, const Epi& E, const int wid_s) {
;     ...
;     for (;;) {
;         const bool has_next = S.next(ui + 1, nxt);
;         const char* nA = has_next ? (const char*)g.A + (size_t)nxt.pm * tstepA : cA; const char* nB = has_next ? (const char*)g.Bt + (size_t)nxt.pn * tstepB : cB;
;         for (int t = 0; t < nt; t += 2) {
;             const bool last = (t == nt - 2);
;             const char* a1 = cA + (size_t)(t + 1) * kstep;
;             const char* a2 = last ? nA : cA + (size_t)(t + 2) * kstep; const char* b2 = last ? nB : cB + (size_t)(t + 2) * kstep;
;             const char* a3 = a2 + kstep; const char* b3 = b2 + kstep;
;             PG8_LDB(B0, 0, 0); PG8_SCHED; PG8_LDA(At, 0, 0); PG8_STAGE(PG8_SA(1, 1), a1 + hstepA, voffA);
;             PG8_WAIT_L(8); PG8_BAR; PG8_WAIT_L(0); PG8_MMA(0, 0, At, B0); PG8_BAR; PG8_SCHED;
;             PG8_LDB(B1, 0, 1); PG8_STAGE(PG8_SB(0, 0), b2, voffB);
;             PG8_BAR; PG8_WAIT_L(0); PG8_MMA(0, 1, At, B1); PG8_BAR;
;             PG8_LDA(At, 0, 1); PG8_STAGE(PG8_SA(0, 0), a2, voffA);
;             PG8_BAR; PG8_WAIT_L(0); PG8_MMA(1, 0, At, B0); PG8_BAR; PG8_SCHED;
;             PG8_STAGE(PG8_SB(0, 1), b2 + hstepB, voffB);
;             PG8_WAIT_V(6); PG8_BAR; PG8_MMA(1, 1, At, B1); PG8_BAR;
;             PG8_LDB(B0, 1, 0); PG8_SCHED; PG8_LDA(At, 1, 0); PG8_STAGE(PG8_SA(0, 1), a2 + hstepA, voffA);
;             PG8_WAIT_L(8); PG8_BAR; PG8_WAIT_L(0); PG8_MMA(0, 0, At, B0); PG8_BAR; PG8_SCHED;
;             PG8_LDB(B1, 1, 1); PG8_STAGE(PG8_SB(1, 0), b3, voffB);
;             PG8_BAR; PG8_WAIT_L(0); PG8_MMA(0, 1, At, B1); PG8_BAR;
;             PG8_LDA(At, 1, 1); PG8_STAGE(PG8_SA(1, 0), a3, voffA);
;             PG8_BAR; PG8_WAIT_L(0); PG8_MMA(1, 0, At, B0); PG8_BAR; PG8_SCHED;
;             PG8_STAGE(PG8_SB(1, 1), b3 + hstepB, voffB);
;             PG8_WAIT_V(6); PG8_BAR; PG8_MMA(1, 1, At, B1); PG8_BAR;
;         }
;         E(acc, cur, wr, wc, fr, fq);
;         if (!has_next) break;
; #pragma unroll
;         for (int a = 0; a < 2; ++a)
; #pragma unroll
;             for (int b = 0; b < 2; ++b)
; #pragma unroll
;                 for (int m = 0; m < 4; ++m)
; #pragma unroll
;                     for (int n = 0; n < 2; ++n) acc[a][b][m][n] = (f32x4){0.f, 0.f, 0.f, 0.f};
.LBB0_1434:
	v_mbcnt_lo_u32_b32 v114, -1, 0
	v_mbcnt_hi_u32_b32 v114, -1, v114
	v_and_b32_e32 v114, 0x30, v114
	v_add_u32_e32 v114, v114, v161
	v_lshl_add_u32 v114, s4, 8, v114
	v_mov_b32_e32 v115, 0
	v_lshl_add_u64 v[114:115], v[114:115], 2, s[14:15]
	s_mov_b64 s[100:101], 0x200
	s_lshr_b32 s98, s63, 1
	s_add_i32 s98, s98, 0x22000
	v_lshl_add_u64 v[116:117], v[114:115], 0, s[100:101]
	s_mov_b32 m0, s98
	s_nop 0
	global_load_lds_dword v[114:115], off
	s_add_i32 m0, s98, 0x100
	s_nop 0
	global_load_lds_dword v[116:117], off
	v_mov_b64_e32 v[2:3], 0x1600
	s_ashr_i32 s43, s42, 31
	v_cmp_lt_i64_e32 vcc, s[44:45], v[2:3]
	s_lshl_b64 s[44:45], s[42:43], 19
	s_add_u32 s44, s55, s44
	s_addc_u32 s45, s56, s45
	s_and_b64 s[46:47], vcc, exec
	s_cselect_b32 s5, s45, s49
	s_cselect_b32 s43, s44, s48
	s_ashr_i32 s41, s40, 31
	s_lshl_b64 s[46:47], s[40:41], 19
	s_add_u32 s46, s57, s46
	s_addc_u32 s47, s62, s47
	s_and_b64 s[52:53], vcc, exec
	s_cselect_b32 s41, s47, s51
	s_cselect_b32 s73, s46, s50
	s_add_u32 s48, s48, 0x40080
	s_addc_u32 s49, s49, 0
	s_add_u32 s76, s50, 0x100
	v_mov_b32_e32 v90, 0
	s_addc_u32 s77, s51, 0
	s_mov_b32 s82, -2
	v_mov_b32_e32 v91, v90
	v_mov_b32_e32 v92, v90
	v_mov_b32_e32 v93, v90
	v_mov_b32_e32 v30, v90
	v_mov_b32_e32 v31, v90
	v_mov_b32_e32 v32, v90
	v_mov_b32_e32 v33, v90
	v_mov_b32_e32 v82, v90
	v_mov_b32_e32 v83, v90
	v_mov_b32_e32 v84, v90
	v_mov_b32_e32 v85, v90
	v_mov_b32_e32 v2, v90
	v_mov_b32_e32 v3, v90
	v_mov_b32_e32 v4, v90
	v_mov_b32_e32 v5, v90
	v_mov_b32_e32 v58, v90
	v_mov_b32_e32 v59, v90
	v_mov_b32_e32 v60, v90
	v_mov_b32_e32 v61, v90
	v_mov_b32_e32 v6, v90
	v_mov_b32_e32 v7, v90
	v_mov_b32_e32 v8, v90
	v_mov_b32_e32 v9, v90
	v_mov_b32_e32 v62, v90
	v_mov_b32_e32 v63, v90
	v_mov_b32_e32 v64, v90
	v_mov_b32_e32 v65, v90
	v_mov_b32_e32 v10, v90
	v_mov_b32_e32 v11, v90
	v_mov_b32_e32 v12, v90
	v_mov_b32_e32 v13, v90
	v_mov_b32_e32 v70, v90
	v_mov_b32_e32 v71, v90
	v_mov_b32_e32 v72, v90
	v_mov_b32_e32 v73, v90
	v_mov_b32_e32 v26, v90
	v_mov_b32_e32 v27, v90
	v_mov_b32_e32 v28, v90
	v_mov_b32_e32 v29, v90
	v_mov_b32_e32 v86, v90
	v_mov_b32_e32 v87, v90
	v_mov_b32_e32 v88, v90
	v_mov_b32_e32 v89, v90
	v_mov_b32_e32 v14, v90
	v_mov_b32_e32 v15, v90
	v_mov_b32_e32 v16, v90
	v_mov_b32_e32 v17, v90
	v_mov_b32_e32 v66, v90
	v_mov_b32_e32 v67, v90
	v_mov_b32_e32 v68, v90
	v_mov_b32_e32 v69, v90
	v_mov_b32_e32 v18, v90
	v_mov_b32_e32 v19, v90
	v_mov_b32_e32 v20, v90
	v_mov_b32_e32 v21, v90
	v_mov_b32_e32 v74, v90
	v_mov_b32_e32 v75, v90
	v_mov_b32_e32 v76, v90
	v_mov_b32_e32 v77, v90
	v_mov_b32_e32 v22, v90
	v_mov_b32_e32 v23, v90
	v_mov_b32_e32 v24, v90
	v_mov_b32_e32 v25, v90
	v_mov_b32_e32 v78, v90
	v_mov_b32_e32 v79, v90
	v_mov_b32_e32 v80, v90
	v_mov_b32_e32 v81, v90
	v_mov_b32_e32 v50, v90
	v_mov_b32_e32 v51, v90
	v_mov_b32_e32 v52, v90
	v_mov_b32_e32 v53, v90
	v_mov_b32_e32 v106, v90
	v_mov_b32_e32 v107, v90
	v_mov_b32_e32 v108, v90
	v_mov_b32_e32 v109, v90
	v_mov_b32_e32 v34, v90
	v_mov_b32_e32 v35, v90
	v_mov_b32_e32 v36, v90
	v_mov_b32_e32 v37, v90
	v_mov_b32_e32 v122, v90
	v_mov_b32_e32 v123, v90
	v_mov_b32_e32 v124, v90
	v_mov_b32_e32 v125, v90
	v_mov_b32_e32 v38, v90
	v_mov_b32_e32 v39, v90
	v_mov_b32_e32 v40, v90
	v_mov_b32_e32 v41, v90
	v_mov_b32_e32 v126, v90
	v_mov_b32_e32 v127, v90
	v_mov_b32_e32 v128, v90
	v_mov_b32_e32 v129, v90
	v_mov_b32_e32 v94, v90
	v_mov_b32_e32 v95, v90
	v_mov_b32_e32 v96, v90
	v_mov_b32_e32 v97, v90
	v_mov_b32_e32 v54, v90
	v_mov_b32_e32 v55, v90
	v_mov_b32_e32 v56, v90
	v_mov_b32_e32 v57, v90
	v_mov_b32_e32 v110, v90
	v_mov_b32_e32 v111, v90
	v_mov_b32_e32 v112, v90
	v_mov_b32_e32 v113, v90
	v_mov_b32_e32 v42, v90
	v_mov_b32_e32 v43, v90
	v_mov_b32_e32 v44, v90
	v_mov_b32_e32 v45, v90
	v_mov_b32_e32 v130, v90
	v_mov_b32_e32 v131, v90
	v_mov_b32_e32 v132, v90
	v_mov_b32_e32 v133, v90
	v_mov_b32_e32 v46, v90
	v_mov_b32_e32 v47, v90
	v_mov_b32_e32 v48, v90
	v_mov_b32_e32 v49, v90
	v_mov_b32_e32 v134, v90
	v_mov_b32_e32 v135, v90
	v_mov_b32_e32 v136, v90
	v_mov_b32_e32 v137, v90
	v_mov_b32_e32 v98, v90
	v_mov_b32_e32 v99, v90
	v_mov_b32_e32 v100, v90
	v_mov_b32_e32 v101, v90
	v_mov_b32_e32 v102, v90
	v_mov_b32_e32 v103, v90
	v_mov_b32_e32 v104, v90
	v_mov_b32_e32 v105, v90

; #define LAS __attribute__((address_space(3)))
;     __device__ __forceinline__ void operator()(const f32x4 (&acc_c)[2][2][4][2], const Unit& u, int wr, int wc, int fr, int fq) const {
;     ...
;         const int row0 = u.pm * BM + wr * 64 + fr, jl = wc * 32 + 8 * fq, ch0 = u.pn * 128 + jl;
;         float rsv[2][4];
; #pragma unroll
;         for (int ai = 0; ai < 2; ++ai)
; #pragma unroll
;             for (int m = 0; m < 4; ++m) rsv[ai][m] = rowsq[row0 + ai * HALF + m * 16];
; #pragma unroll
;         for (int ai = 0; ai < 2; ++ai)
; #pragma unroll
;             for (int m = 0; m < 4; ++m) { const float rs = rsqrtf(rsv[ai][m] * (1.0f / 1024.0f) + EPS);
; #pragma unroll
;                 for (int bj = 0; bj < 2; ++bj)
; #pragma unroll
;                     for (int n = 0; n < 2; ++n) acc[ai][bj][m][n] *= rs; }
;         if (fr >= 14) {
; #pragma unroll
;             for (int ai = 0; ai < 2; ++ai)
; #pragma unroll
;                 for (int bj = 0; bj < 2; ++bj)
; #pragma unroll
;                     for (int n = 0; n < 2; ++n) *(LAS f32x4*)(xch + ((ai * 2 + wr) * 4 + wc) * 128 + (fr - 14) * 64 + bj * 32 + 8 * fq + 4 * n) = acc[ai][bj][3][n];
;         }
;     ...
;             for (int t = 0; t < 3; ++t) { wg[t] = *(const f32x4*)(cw + t * FF2 + ch0 + 4 * n); wv[t] = *(const f32x4*)(cw + t * FF2 + FF + ch0 + 4 * n); }
;             bg = *(const f32x4*)(cb + ch0 + 4 * n); bv = *(const f32x4*)(cb + FF + ch0 + 4 * n);
.Lalign_up_a:
	v_lshl_or_b32 v250, s72, 7, v170
	v_ashrrev_i32_e32 v251, 31, v250
	v_lshlrev_b64 v[250:251], 2, v[250:251]
	v_lshl_add_u64 v[242:243], s[16:17], 0, v[250:251]
	global_load_dword v241, v[242:243], off
	v_lshl_add_u64 v[242:243], s[26:27], 0, v[250:251]
	global_load_dword v241, v[242:243], off
	v_lshl_add_u64 v[242:243], s[28:29], 0, v[250:251]
	global_load_dword v241, v[242:243], off
	v_lshl_add_u64 v[242:243], s[30:31], 0, v[250:251]
	global_load_dword v241, v[242:243], off
	v_lshl_add_u64 v[242:243], s[34:35], 0, v[250:251]
	global_load_dword v241, v[242:243], off
	v_lshl_add_u64 v[242:243], s[36:37], 0, v[250:251]
	global_load_dword v241, v[242:243], off
	v_lshl_add_u64 v[242:243], s[18:19], 0, v[250:251]
	global_load_dword v241, v[242:243], off
	v_lshl_add_u64 v[242:243], s[38:39], 0, v[250:251]
	global_load_dword v241, v[242:243], off
	v_lshl_add_u32 v192, s4, 8, v161
	v_or_b32_e32 v198, 16, v192
	v_ashrrev_i32_e32 v193, 31, v192
	v_ashrrev_i32_e32 v199, 31, v198
	v_or_b32_e32 v196, 32, v192
	v_lshl_add_u64 v[114:115], v[192:193], 2, s[14:15]
	v_lshl_add_u64 v[116:117], v[198:199], 2, s[14:15]
	v_ashrrev_i32_e32 v197, 31, v196
	v_or_b32_e32 v194, 48, v192
	s_lshr_b32 s98, s63, 1
	s_add_i32 s98, s98, 0x22000
	v_and_b32_e32 v250, 15, v161
	v_lshl_add_u32 v250, v250, 2, s98
	ds_read_b32 v0, v250
	ds_read_b32 v190, v250 offset:64
	v_lshl_add_u64 v[116:117], v[196:197], 2, s[14:15]
	v_ashrrev_i32_e32 v195, 31, v194
	ds_read_b32 v147, v250 offset:128
	v_lshl_add_u64 v[116:117], v[194:195], 2, s[14:15]
	ds_read_b32 v116, v250 offset:192
	s_nop 0
	ds_read_b32 v195, v250 offset:256
	ds_read_b32 v193, v250 offset:320
	ds_read_b32 v191, v250 offset:384
	s_nop 0
	ds_read_b32 v115, v250 offset:448
	s_waitcnt lgkmcnt(0)
	v_fmamk_f32 v114, v116, 0x3a800000, v216
	v_cmp_gt_f32_e32 vcc, s2, v114
	v_mul_f32_e32 v116, 0x4b800000, v114
	s_nop 0
	v_cndmask_b32_e32 v114, v114, v116, vcc
	v_rsq_f32_e32 v114, v114
	s_nop 0
	v_mul_f32_e32 v116, 0x45800000, v114
	v_cndmask_b32_e32 v114, v114, v116, vcc
	v_pk_mul_f32 v[138:139], v[106:107], v[114:115] op_sel_hi:[1,0]
	v_fmamk_f32 v106, v115, 0x3a800000, v216
	v_cmp_gt_f32_e32 vcc, s2, v106
	v_mul_f32_e32 v107, 0x4b800000, v106
	v_pk_mul_f32 v[144:145], v[112:113], v[114:115] op_sel_hi:[1,0]
	v_cndmask_b32_e32 v106, v106, v107, vcc
	v_rsq_f32_e32 v106, v106
	v_pk_mul_f32 v[142:143], v[110:111], v[114:115] op_sel_hi:[1,0]
	v_pk_mul_f32 v[56:57], v[56:57], v[114:115] op_sel_hi:[1,0]
	v_pk_mul_f32 v[54:55], v[54:55], v[114:115] op_sel_hi:[1,0]
	v_mul_f32_e32 v107, 0x45800000, v106
	v_cndmask_b32_e32 v106, v106, v107, vcc
	v_pk_mul_f32 v[140:141], v[108:109], v[114:115] op_sel_hi:[1,0]
	v_pk_mul_f32 v[52:53], v[52:53], v[114:115] op_sel_hi:[1,0]
	v_pk_mul_f32 v[50:51], v[50:51], v[114:115] op_sel_hi:[1,0]
	v_pk_mul_f32 v[88:89], v[88:89], v[106:107] op_sel_hi:[1,0]
	v_pk_mul_f32 v[86:87], v[86:87], v[106:107] op_sel_hi:[1,0]
	v_pk_mul_f32 v[28:29], v[28:29], v[106:107] op_sel_hi:[1,0]
	v_pk_mul_f32 v[26:27], v[26:27], v[106:107] op_sel_hi:[1,0]
	v_pk_mul_f32 v[84:85], v[84:85], v[106:107] op_sel_hi:[1,0]
	v_pk_mul_f32 v[82:83], v[82:83], v[106:107] op_sel_hi:[1,0]
	v_pk_mul_f32 v[32:33], v[32:33], v[106:107] op_sel_hi:[1,0]
	v_pk_mul_f32 v[30:31], v[30:31], v[106:107] op_sel_hi:[1,0]
	s_and_saveexec_b64 s[48:49], s[6:7]
	s_cbranch_execz .LBB0_1438
	ds_write_b128 v228, v[142:145]
	ds_write_b128 v229, v[54:57]
	ds_write_b128 v230, v[138:141]
	ds_write_b128 v231, v[50:53]
	ds_write_b128 v227, v[86:89] offset:512
	ds_write_b128 v227, v[26:29] offset:528
	ds_write_b128 v227, v[82:85] offset:640
	ds_write_b128 v227, v[30:33] offset:656
